# LRU fix-up loop: 12 loads per iteration in flight with counted waits (was load-wait-compute-store per step)
# speedup vs baseline: 1.0354x; 1.0065x over previous
; __device__ __forceinline__ unsigned cvt_pk_bf16(float lo, float hi) { unsigned r; asm volatile("v_cvt_pk_bf16_f32 %0, %1, %2" : "=v"(r) : "v"(lo), "v"(hi)); return r; }
; __device__ __forceinline__ void lru_fix_item(const Args& a, const int seg, const int hb, const int tid_in) {
;     ...
; #pragma unroll 4
;     for (int i = 0; i < SEGLEN / 64; ++i) { const size_t off = (size_t)(seg * SEGLEN + r0 + 64 * i) * D + cch;
;         const u32x4 hl = *(const u32x4*)(HL + off), pp = *(const u32x4*)(PB + off), gg = *(const u32x4*)(GATE + off);
;         u32x4 o; const unsigned* hw = (const unsigned*)&hl; const unsigned* pw = (const unsigned*)&pp; const unsigned* gw = (const unsigned*)&gg; unsigned* ow = (unsigned*)&o;
; #pragma unroll
;         for (int e = 0; e < 4; ++e) { const float y0 = (__uint_as_float(hw[e] << 16) + __uint_as_float(pw[e] << 16) * hin[2 * e]) * __uint_as_float(gw[e] << 16);
;             const float y1 = (__uint_as_float(hw[e] & 0xffff0000u) + __uint_as_float(pw[e] & 0xffff0000u) * hin[2 * e + 1]) * __uint_as_float(gw[e] & 0xffff0000u);
;             ow[e] = cvt_pk_bf16(y0, y1); }
;         *(u32x4*)(YL + (size_t)(seg * SEGLEN + r0 + 64 * i) * (2 * D) + cch) = o; }
.LBB0_423:
	s_nop 0
	v_add_u32_e32 v2, s0, v1
	v_mov_b32_e32 v4, v2
	v_ashrrev_i32_e32 v5, 31, v4
	v_lshlrev_b64 v[4:5], 11, v[4:5]
	v_or_b32_e32 v4, v4, v18
	v_lshl_add_u64 v[6:7], s[26:27], 0, v[4:5]
	global_load_dwordx4 v[200:203], v[6:7], off
	v_lshl_add_u64 v[6:7], s[28:29], 0, v[4:5]
	global_load_dwordx4 v[204:207], v[6:7], off
	v_lshl_add_u64 v[6:7], s[30:31], 0, v[4:5]
	global_load_dwordx4 v[208:211], v[6:7], off
	v_add_u32_e32 v4, 64, v2
	v_ashrrev_i32_e32 v5, 31, v4
	v_lshlrev_b64 v[4:5], 11, v[4:5]
	v_or_b32_e32 v4, v4, v18
	v_lshl_add_u64 v[6:7], s[26:27], 0, v[4:5]
	global_load_dwordx4 v[212:215], v[6:7], off
	v_lshl_add_u64 v[6:7], s[28:29], 0, v[4:5]
	global_load_dwordx4 v[216:219], v[6:7], off
	v_lshl_add_u64 v[6:7], s[30:31], 0, v[4:5]
	global_load_dwordx4 v[220:223], v[6:7], off
	v_add_u32_e32 v4, 128, v2
	v_ashrrev_i32_e32 v5, 31, v4
	v_lshlrev_b64 v[4:5], 11, v[4:5]
	v_or_b32_e32 v4, v4, v18
	v_lshl_add_u64 v[6:7], s[26:27], 0, v[4:5]
	global_load_dwordx4 v[224:227], v[6:7], off
	v_lshl_add_u64 v[6:7], s[28:29], 0, v[4:5]
	global_load_dwordx4 v[228:231], v[6:7], off
	v_lshl_add_u64 v[6:7], s[30:31], 0, v[4:5]
	global_load_dwordx4 v[232:235], v[6:7], off
	v_add_u32_e32 v4, 192, v2
	v_ashrrev_i32_e32 v5, 31, v4
	v_lshlrev_b64 v[4:5], 11, v[4:5]
	v_or_b32_e32 v4, v4, v18
	v_lshl_add_u64 v[6:7], s[26:27], 0, v[4:5]
	global_load_dwordx4 v[236:239], v[6:7], off
	v_lshl_add_u64 v[6:7], s[28:29], 0, v[4:5]
	global_load_dwordx4 v[240:243], v[6:7], off
	v_lshl_add_u64 v[6:7], s[30:31], 0, v[4:5]
	global_load_dwordx4 v[244:247], v[6:7], off
	s_waitcnt vmcnt(9)
	v_lshlrev_b32_e32 v8, 16, v200
	v_and_b32_e32 v200, 0xffff0000, v200
	v_lshlrev_b32_e32 v9, 16, v204
	v_fmac_f32_e32 v8, v10, v9
	v_lshlrev_b32_e32 v9, 16, v208
	v_mul_f32_e32 v8, v8, v9
	v_and_b32_e32 v9, 0xffff0000, v204
	v_fmac_f32_e32 v200, v11, v9
	v_and_b32_e32 v9, 0xffff0000, v208
	v_mul_f32_e32 v200, v200, v9
	v_cvt_pk_bf16_f32 v200, v8, v200
	v_lshlrev_b32_e32 v8, 16, v201
	v_and_b32_e32 v201, 0xffff0000, v201
	v_lshlrev_b32_e32 v9, 16, v205
	v_fmac_f32_e32 v8, v14, v9
	v_lshlrev_b32_e32 v9, 16, v209
	v_mul_f32_e32 v8, v8, v9
	v_and_b32_e32 v9, 0xffff0000, v205
	v_fmac_f32_e32 v201, v15, v9
	v_and_b32_e32 v9, 0xffff0000, v209
	v_mul_f32_e32 v201, v201, v9
	v_cvt_pk_bf16_f32 v201, v8, v201
	v_lshlrev_b32_e32 v8, 16, v202
	v_and_b32_e32 v202, 0xffff0000, v202
	v_lshlrev_b32_e32 v9, 16, v206
	v_fmac_f32_e32 v8, v16, v9
	v_lshlrev_b32_e32 v9, 16, v210
	v_mul_f32_e32 v8, v8, v9
	v_and_b32_e32 v9, 0xffff0000, v206
	v_fmac_f32_e32 v202, v17, v9
	v_and_b32_e32 v9, 0xffff0000, v210
	v_mul_f32_e32 v202, v202, v9
	v_cvt_pk_bf16_f32 v202, v8, v202
	v_lshlrev_b32_e32 v8, 16, v203
	v_and_b32_e32 v203, 0xffff0000, v203
	v_lshlrev_b32_e32 v9, 16, v207
	v_fmac_f32_e32 v8, v12, v9
	v_lshlrev_b32_e32 v9, 16, v211
	v_mul_f32_e32 v8, v8, v9
	v_and_b32_e32 v9, 0xffff0000, v207
	v_fmac_f32_e32 v203, v13, v9
	v_and_b32_e32 v9, 0xffff0000, v211
	v_mul_f32_e32 v203, v203, v9
	v_cvt_pk_bf16_f32 v203, v8, v203
	v_mov_b32_e32 v4, v2
	v_ashrrev_i32_e32 v5, 31, v4
	v_lshlrev_b64 v[4:5], 12, v[4:5]
	v_lshl_add_u64 v[4:5], v[20:21], 0, v[4:5]
	global_store_dwordx4 v[4:5], v[200:203], off
	s_waitcnt vmcnt(7)
	v_lshlrev_b32_e32 v8, 16, v212
	v_and_b32_e32 v212, 0xffff0000, v212
	v_lshlrev_b32_e32 v9, 16, v216
	v_fmac_f32_e32 v8, v10, v9
	v_lshlrev_b32_e32 v9, 16, v220
	v_mul_f32_e32 v8, v8, v9
	v_and_b32_e32 v9, 0xffff0000, v216
	v_fmac_f32_e32 v212, v11, v9
	v_and_b32_e32 v9, 0xffff0000, v220
	v_mul_f32_e32 v212, v212, v9
	v_cvt_pk_bf16_f32 v212, v8, v212
	v_lshlrev_b32_e32 v8, 16, v213
	v_and_b32_e32 v213, 0xffff0000, v213
	v_lshlrev_b32_e32 v9, 16, v217
	v_fmac_f32_e32 v8, v14, v9
	v_lshlrev_b32_e32 v9, 16, v221
	v_mul_f32_e32 v8, v8, v9
	v_and_b32_e32 v9, 0xffff0000, v217
	v_fmac_f32_e32 v213, v15, v9
	v_and_b32_e32 v9, 0xffff0000, v221
	v_mul_f32_e32 v213, v213, v9
	v_cvt_pk_bf16_f32 v213, v8, v213
	v_lshlrev_b32_e32 v8, 16, v214
	v_and_b32_e32 v214, 0xffff0000, v214
	v_lshlrev_b32_e32 v9, 16, v218
	v_fmac_f32_e32 v8, v16, v9
	v_lshlrev_b32_e32 v9, 16, v222
	v_mul_f32_e32 v8, v8, v9
	v_and_b32_e32 v9, 0xffff0000, v218
	v_fmac_f32_e32 v214, v17, v9
	v_and_b32_e32 v9, 0xffff0000, v222
	v_mul_f32_e32 v214, v214, v9
	v_cvt_pk_bf16_f32 v214, v8, v214
	v_lshlrev_b32_e32 v8, 16, v215
	v_and_b32_e32 v215, 0xffff0000, v215
	v_lshlrev_b32_e32 v9, 16, v219
	v_fmac_f32_e32 v8, v12, v9
	v_lshlrev_b32_e32 v9, 16, v223
	v_mul_f32_e32 v8, v8, v9
	v_and_b32_e32 v9, 0xffff0000, v219
	v_fmac_f32_e32 v215, v13, v9
	v_and_b32_e32 v9, 0xffff0000, v223
	v_mul_f32_e32 v215, v215, v9
	v_cvt_pk_bf16_f32 v215, v8, v215
	v_add_u32_e32 v4, 64, v2
	v_ashrrev_i32_e32 v5, 31, v4
	v_lshlrev_b64 v[4:5], 12, v[4:5]
	v_lshl_add_u64 v[4:5], v[20:21], 0, v[4:5]
	global_store_dwordx4 v[4:5], v[212:215], off
	s_waitcnt vmcnt(5)
; __device__ __forceinline__ unsigned cvt_pk_bf16(float lo, float hi) { unsigned r; asm volatile("v_cvt_pk_bf16_f32 %0, %1, %2" : "=v"(r) : "v"(lo), "v"(hi)); return r; }
; __device__ __forceinline__ void lru_fix_item(const Args& a, const int seg, const int hb, const int tid_in) {
;     ...
;     for (int i = 0; i < SEGLEN / 64; ++i) { const size_t off = (size_t)(seg * SEGLEN + r0 + 64 * i) * D + cch;
;         const u32x4 hl = *(const u32x4*)(HL + off), pp = *(const u32x4*)(PB + off), gg = *(const u32x4*)(GATE + off);
;         u32x4 o; const unsigned* hw = (const unsigned*)&hl; const unsigned* pw = (const unsigned*)&pp; const unsigned* gw = (const unsigned*)&gg; unsigned* ow = (unsigned*)&o;
; #pragma unroll
;         for (int e = 0; e < 4; ++e) { const float y0 = (__uint_as_float(hw[e] << 16) + __uint_as_float(pw[e] << 16) * hin[2 * e]) * __uint_as_float(gw[e] << 16);
;             const float y1 = (__uint_as_float(hw[e] & 0xffff0000u) + __uint_as_float(pw[e] & 0xffff0000u) * hin[2 * e + 1]) * __uint_as_float(gw[e] & 0xffff0000u);
;             ow[e] = cvt_pk_bf16(y0, y1); }
;         *(u32x4*)(YL + (size_t)(seg * SEGLEN + r0 + 64 * i) * (2 * D) + cch) = o; }
	v_lshlrev_b32_e32 v8, 16, v224
	v_and_b32_e32 v224, 0xffff0000, v224
	v_lshlrev_b32_e32 v9, 16, v228
	v_fmac_f32_e32 v8, v10, v9
	v_lshlrev_b32_e32 v9, 16, v232
	v_mul_f32_e32 v8, v8, v9
	v_and_b32_e32 v9, 0xffff0000, v228
	v_fmac_f32_e32 v224, v11, v9
	v_and_b32_e32 v9, 0xffff0000, v232
	v_mul_f32_e32 v224, v224, v9
	v_cvt_pk_bf16_f32 v224, v8, v224
	v_lshlrev_b32_e32 v8, 16, v225
	v_and_b32_e32 v225, 0xffff0000, v225
	v_lshlrev_b32_e32 v9, 16, v229
	v_fmac_f32_e32 v8, v14, v9
	v_lshlrev_b32_e32 v9, 16, v233
	v_mul_f32_e32 v8, v8, v9
	v_and_b32_e32 v9, 0xffff0000, v229
	v_fmac_f32_e32 v225, v15, v9
	v_and_b32_e32 v9, 0xffff0000, v233
	v_mul_f32_e32 v225, v225, v9
	v_cvt_pk_bf16_f32 v225, v8, v225
	v_lshlrev_b32_e32 v8, 16, v226
	v_and_b32_e32 v226, 0xffff0000, v226
	v_lshlrev_b32_e32 v9, 16, v230
	v_fmac_f32_e32 v8, v16, v9
	v_lshlrev_b32_e32 v9, 16, v234
	v_mul_f32_e32 v8, v8, v9
	v_and_b32_e32 v9, 0xffff0000, v230
	v_fmac_f32_e32 v226, v17, v9
	v_and_b32_e32 v9, 0xffff0000, v234
	v_mul_f32_e32 v226, v226, v9
	v_cvt_pk_bf16_f32 v226, v8, v226
	v_lshlrev_b32_e32 v8, 16, v227
	v_and_b32_e32 v227, 0xffff0000, v227
	v_lshlrev_b32_e32 v9, 16, v231
	v_fmac_f32_e32 v8, v12, v9
	v_lshlrev_b32_e32 v9, 16, v235
	v_mul_f32_e32 v8, v8, v9
	v_and_b32_e32 v9, 0xffff0000, v231
	v_fmac_f32_e32 v227, v13, v9
	v_and_b32_e32 v9, 0xffff0000, v235
	v_mul_f32_e32 v227, v227, v9
	v_cvt_pk_bf16_f32 v227, v8, v227
	v_add_u32_e32 v4, 128, v2
	v_ashrrev_i32_e32 v5, 31, v4
	v_lshlrev_b64 v[4:5], 12, v[4:5]
	v_lshl_add_u64 v[4:5], v[20:21], 0, v[4:5]
	global_store_dwordx4 v[4:5], v[224:227], off
	s_waitcnt vmcnt(3)
	v_lshlrev_b32_e32 v8, 16, v236
	v_and_b32_e32 v236, 0xffff0000, v236
	v_lshlrev_b32_e32 v9, 16, v240
	v_fmac_f32_e32 v8, v10, v9
	v_lshlrev_b32_e32 v9, 16, v244
	v_mul_f32_e32 v8, v8, v9
	v_and_b32_e32 v9, 0xffff0000, v240
	v_fmac_f32_e32 v236, v11, v9
	v_and_b32_e32 v9, 0xffff0000, v244
	v_mul_f32_e32 v236, v236, v9
	v_cvt_pk_bf16_f32 v236, v8, v236
	v_lshlrev_b32_e32 v8, 16, v237
	v_and_b32_e32 v237, 0xffff0000, v237
	v_lshlrev_b32_e32 v9, 16, v241
	v_fmac_f32_e32 v8, v14, v9
	v_lshlrev_b32_e32 v9, 16, v245
	v_mul_f32_e32 v8, v8, v9
	v_and_b32_e32 v9, 0xffff0000, v241
	v_fmac_f32_e32 v237, v15, v9
	v_and_b32_e32 v9, 0xffff0000, v245
	v_mul_f32_e32 v237, v237, v9
	v_cvt_pk_bf16_f32 v237, v8, v237
	v_lshlrev_b32_e32 v8, 16, v238
	v_and_b32_e32 v238, 0xffff0000, v238
	v_lshlrev_b32_e32 v9, 16, v242
	v_fmac_f32_e32 v8, v16, v9
	v_lshlrev_b32_e32 v9, 16, v246
	v_mul_f32_e32 v8, v8, v9
	v_and_b32_e32 v9, 0xffff0000, v242
	v_fmac_f32_e32 v238, v17, v9
	v_and_b32_e32 v9, 0xffff0000, v246
	v_mul_f32_e32 v238, v238, v9
	v_cvt_pk_bf16_f32 v238, v8, v238
	v_lshlrev_b32_e32 v8, 16, v239
	v_and_b32_e32 v239, 0xffff0000, v239
	v_lshlrev_b32_e32 v9, 16, v243
	v_fmac_f32_e32 v8, v12, v9
	v_lshlrev_b32_e32 v9, 16, v247
	v_mul_f32_e32 v8, v8, v9
	v_and_b32_e32 v9, 0xffff0000, v243
	v_fmac_f32_e32 v239, v13, v9
	v_and_b32_e32 v9, 0xffff0000, v247
	v_mul_f32_e32 v239, v239, v9
	v_cvt_pk_bf16_f32 v239, v8, v239
	v_add_u32_e32 v4, 192, v2
	v_ashrrev_i32_e32 v5, 31, v4
	v_lshlrev_b64 v[4:5], 12, v[4:5]
	v_lshl_add_u64 v[4:5], v[20:21], 0, v[4:5]
	global_store_dwordx4 v[4:5], v[236:239], off
	s_addk_i32 s0, 0x100
	s_cmpk_eq_i32 s0, 0x400
	s_cbranch_scc0 .LBB0_423
	s_mov_b64 s[0:1], 0
